# v51 + first K iteration after an act epilogue tolerates its 16 stores (run 1)
# speedup vs baseline: 1.0101x; 1.0101x over previous
; #define LAS __attribute__((address_space(3)))
; __global__ void __launch_bounds__(512, 2) mega_fwd(Params p) {
;     extern __shared__ __attribute__((aligned(16))) unsigned char lds_raw[];
;     Frame F;
;     F.lds = (LAS unsigned char*)lds_raw; F.MISC = (volatile LAS unsigned*)(F.lds + LDS_MISC);
;     F.wave = __builtin_amdgcn_readfirstlane((int)threadIdx.x >> 6);
;     F.G = gridDim.x; { const int bx = blockIdx.x; F.vcu = (F.G % 8 == 0) ? (bx % 8) * (F.G / 8) + bx / 8 : bx; }
;     if (threadIdx.x < 64) F.MISC[threadIdx.x] = 0u;
_Z8mega_fwd6Params:
	s_mov_b32 s99, 0
	s_mov_b32 s101, s2
	s_mov_b32 s100, 0
	s_load_dword s3, s[0:1], 0xa0
	s_add_u32 s4, s0, 0xa0
	s_addc_u32 s5, s1, 0
	v_readfirstlane_b32 s34, v0
	v_writelane_b32 v243, s4, 0
	s_waitcnt lgkmcnt(0)
	s_mov_b32 s8, s3
	s_and_b32 s3, s3, 7
	s_cmp_lg_u32 s3, 0
	s_mov_b32 s60, s2
	s_mov_b32 s3, s2
	v_writelane_b32 v243, s5, 1
	s_cbranch_scc0 .LBB0_29
	s_load_dwordx2 s[64:65], s[0:1], 0x98
	v_cmp_gt_u32_e32 vcc, 64, v0
	s_and_saveexec_b64 s[4:5], vcc

; #define GAS __attribute__((address_space(1)))
;     __device__ __forceinline__ GAS float* outp() const { return (GAS float*)rd(17); }
;     __device__ __forceinline__ GAS unsigned char* wsp() const { return (GAS unsigned char*)rd(18); }
; #define F_qng F.in(9)
; __global__ void __launch_bounds__(512, 2) mega_fwd(Params p) {
;     ...
;         if (IN(pb + 1)) { pg8::Gemm g{(const GAS bf16*)(F.wsp() + WS_XN), (const GAS bf16*)(F.wsp() + WS_WIN) + (size_t)l * NPROJ * D, 0, 0, MTOT / 256, NPROJ / 256, 1, D, 0, WGM_PROJ};
;             pg8::Order S; S.init(g, F.G, (int)blockIdx.x);
;             pg8::EpiProj E{l, F.wsp(), F.outp(), F_qng + l * 128, F_kng + l * 128, (const GAS float*)(F.wsp() + WS_LB) + l * 1024};
;             pg8::gemm_phase(F.lds, g, S, E, F.wave);
.LBB0_172:
	s_mov_b32 s99, 0
	s_cmpk_lt_u32 s101, 0xd4
	s_cbranch_scc1 .Lip_nodelay
	s_movk_i32 s100, 4

; #define GAS __attribute__((address_space(1)))
; #define PG8_STAGE(bufoff, gbase, voff) do { _Pragma("unroll") for (int _i = 0; _i < 2; ++_i) \
;         __builtin_amdgcn_global_load_lds((const GAS unsigned*)((const GAS char*)(gbase) + (voff)[_i]), (LAS unsigned*)(lds + (bufoff) + ldsw + _i * 8192), 16, 0, 0); } while (0)
; #define PG8_LDA(dst, b, h) do { _Pragma("unroll") for (int m = 0; m < 4; ++m) _Pragma("unroll") for (int k = 0; k < 2; ++k) dst[m][k] = *(const LAS bf16x8*)(lds + PG8_SA(b, h) + aoff + m * 2048 + k * 1024); } while (0)
; #define PG8_LDB(dst, b, h) do { _Pragma("unroll") for (int n = 0; n < 2; ++n) _Pragma("unroll") for (int k = 0; k < 2; ++k) dst[n][k] = *(const LAS bf16x8*)(lds + PG8_SB(b, h) + boff + n * 2048 + k * 1024); } while (0)
; #define PG8_MMA(ai, bj, At, Bt) do { __builtin_amdgcn_s_setprio(1); _Pragma("unroll") for (int m = 0; m < 4; ++m) _Pragma("unroll") for (int n = 0; n < 2; ++n) _Pragma("unroll") for (int k = 0; k < 2; ++k) \
;         acc[ai][bj][m][n] = __builtin_amdgcn_mfma_f32_16x16x32_bf16(Bt[n][k], At[m][k], acc[ai][bj][m][n], 0, 0, 0); __builtin_amdgcn_s_setprio(0); } while (0)
; #define PG8_WAIT_V(n) asm volatile("s_waitcnt vmcnt(" #n ")" ::: "memory")
; #define PG8_WAIT_L(n) asm volatile("s_waitcnt lgkmcnt(" #n ")" ::: "memory")
; #define PG8_BAR __builtin_amdgcn_s_barrier()
; #define PG8_SCHED __builtin_amdgcn_sched_barrier(0)
;     ...
;         const GAS char* nA = has_next ? (const GAS char*)(g.A + (size_t)nxt.seg * g.a_seg) + (size_t)nxt.pm * tstep + (MODE ? (size_t)nxt.k0 * kstep : 0) : cA; const GAS char* nB = has_next ? (const GAS char*)(g.Bt + (size_t)nxt.seg * g.b_seg) + (size_t)nxt.pn * tstep + (MODE ? (size_t)nxt.k0 * kstep : 0) : cB;
;         const int nt = MODE == 0 ? K / BK : cur.nk;
;         for (int t = 0; t < nt; t += 2) {
;             const bool last = (t == nt - 2);
;             const GAS char* a1 = cA + (size_t)(t + 1) * kstep;
;             const GAS char* a2 = last ? nA : cA + (size_t)(t + 2) * kstep; const GAS char* b2 = last ? nB : cB + (size_t)(t + 2) * kstep;
;             const GAS char* a3 = a2 + kstep; const GAS char* b3 = b2 + kstep;
;             PG8_LDB(B0, 0, 0); PG8_LDB(B1, 0, 1); PG8_SCHED; PG8_LDA(At, 0, 0); PG8_STAGE(PG8_SA(1, 1), a1 + hstep, voffA);
;             PG8_WAIT_V(8); PG8_WAIT_L(0); PG8_BAR; PG8_MMA(0, 0, At, B0); PG8_MMA(0, 1, At, B1); PG8_BAR; PG8_SCHED;
.LBB0_189:
	s_ashr_i32 s89, s88, 31
	s_lshl_b64 s[8:9], s[88:89], 19
	s_add_u32 s8, s13, s8
	s_addc_u32 s9, s14, s9
	s_and_b64 s[26:27], s[60:61], exec
	s_cselect_b32 s17, s9, s37
	s_cselect_b32 s20, s8, s36
	s_ashr_i32 s93, s92, 31
	s_lshl_b64 s[26:27], s[92:93], 19
	s_add_u32 s26, s15, s26
	s_addc_u32 s27, s68, s27
	s_and_b64 s[52:53], s[60:61], exec
	s_cselect_b32 s25, s27, s35
	s_cselect_b32 s62, s26, s34
	s_add_u32 s63, s34, 0x100
	s_addc_u32 s64, s35, 0
	s_add_u32 s34, s36, 0x40080
	s_addc_u32 s35, s37, 0
	s_mov_b32 s65, -2
	s_add_u32 s36, s34, 0xfffc0080
	s_addc_u32 s37, s35, -1
	s_add_i32 s75, 0, 0x10000
	s_cmp_eq_u32 s65, 12
	s_cselect_b32 s53, s17, s37
	s_cselect_b32 s52, s20, s36
	s_cselect_b32 s37, s25, s64
	s_cselect_b32 s36, s62, s63
	s_add_i32 s89, 0, 0x14000
	v_add_u32_e32 v156, s75, v218
	v_add_u32_e32 v172, s89, v218
	ds_read_b128 v[128:131], v156
	ds_read_b128 v[132:135], v156 offset:1024
	ds_read_b128 v[152:155], v156 offset:2048
	ds_read_b128 v[156:159], v156 offset:3072
	ds_read_b128 v[160:163], v172
	ds_read_b128 v[164:167], v172 offset:1024
	ds_read_b128 v[168:171], v172 offset:2048
	ds_read_b128 v[182:185], v172 offset:3072
	v_lshl_add_u64 v[230:231], s[34:35], 0, v[150:151]
	s_add_i32 m0, s56, 0xc000
	ds_read_b128 v[186:189], v220
	ds_read_b128 v[190:193], v220 offset:1024
	ds_read_b128 v[194:197], v220 offset:2048
	ds_read_b128 v[198:201], v220 offset:3072
	ds_read_b128 v[202:205], v220 offset:4096
	ds_read_b128 v[206:209], v220 offset:5120
	ds_read_b128 v[222:225], v220 offset:6144
	ds_read_b128 v[226:229], v220 offset:7168
	global_load_lds_dwordx4 v[230:231], off
	v_lshl_add_u64 v[230:231], s[34:35], 0, v[148:149]
	s_add_i32 m0, s56, 0xe000
	s_nop 0
	global_load_lds_dwordx4 v[230:231], off
	s_cmp_lg_u32 s99, 0
	s_cbranch_scc1 .Lrx1a
	s_waitcnt vmcnt(8)
	s_branch .Lrx1b

; #define PG8_STAGE(bufoff, gbase, voff) do { _Pragma("unroll") for (int _i = 0; _i < 2; ++_i) \
;         __builtin_amdgcn_global_load_lds((const GAS unsigned*)((const GAS char*)(gbase) + (voff)[_i]), (LAS unsigned*)(lds + (bufoff) + ldsw + _i * 8192), 16, 0, 0); } while (0)
; #define PG8_LDA(dst, b, h) do { _Pragma("unroll") for (int m = 0; m < 4; ++m) _Pragma("unroll") for (int k = 0; k < 2; ++k) dst[m][k] = *(const LAS bf16x8*)(lds + PG8_SA(b, h) + aoff + m * 2048 + k * 1024); } while (0)
; #define PG8_MMA(ai, bj, At, Bt) do { __builtin_amdgcn_s_setprio(1); _Pragma("unroll") for (int m = 0; m < 4; ++m) _Pragma("unroll") for (int n = 0; n < 2; ++n) _Pragma("unroll") for (int k = 0; k < 2; ++k) \
;         acc[ai][bj][m][n] = __builtin_amdgcn_mfma_f32_16x16x32_bf16(Bt[n][k], At[m][k], acc[ai][bj][m][n], 0, 0, 0); __builtin_amdgcn_s_setprio(0); } while (0)
; #define PG8_WAIT_V(n) asm volatile("s_waitcnt vmcnt(" #n ")" ::: "memory")
; #define PG8_WAIT_L(n) asm volatile("s_waitcnt lgkmcnt(" #n ")" ::: "memory")
; #define PG8_BAR __builtin_amdgcn_s_barrier()
; #define PG8_SCHED __builtin_amdgcn_sched_barrier(0)
;     ...
;             PG8_WAIT_V(8); PG8_WAIT_L(0); PG8_BAR; PG8_MMA(0, 0, At, B0); PG8_MMA(0, 1, At, B1); PG8_BAR; PG8_SCHED;
;             PG8_LDA(At, 0, 1); PG8_STAGE(PG8_SB(0, 0), b2, voffB); PG8_STAGE(PG8_SB(0, 1), b2 + hstep, voffB); PG8_STAGE(PG8_SA(0, 0), a2, voffA);
.Lrx1b:
	s_waitcnt lgkmcnt(0)
	s_barrier
	s_setprio 1
	s_waitcnt lgkmcnt(0)
	v_mfma_f32_16x16x32_bf16 v[124:127], v[128:131], v[186:189], 0
	v_mfma_f32_16x16x32_bf16 v[120:123], v[152:155], v[186:189], 0
	v_mfma_f32_16x16x32_bf16 v[108:111], v[128:131], v[194:197], 0
	v_mfma_f32_16x16x32_bf16 v[104:107], v[152:155], v[194:197], 0
	v_mfma_f32_16x16x32_bf16 v[92:95], v[128:131], v[202:205], 0
	v_mfma_f32_16x16x32_bf16 v[88:91], v[152:155], v[202:205], 0
	v_mfma_f32_16x16x32_bf16 v[76:79], v[128:131], v[222:225], 0
	v_mfma_f32_16x16x32_bf16 v[72:75], v[152:155], v[222:225], 0
	v_mfma_f32_16x16x32_bf16 v[124:127], v[132:135], v[190:193], v[124:127]
	v_mfma_f32_16x16x32_bf16 v[120:123], v[156:159], v[190:193], v[120:123]
	v_mfma_f32_16x16x32_bf16 v[108:111], v[132:135], v[198:201], v[108:111]
	v_mfma_f32_16x16x32_bf16 v[104:107], v[156:159], v[198:201], v[104:107]
	v_mfma_f32_16x16x32_bf16 v[92:95], v[132:135], v[206:209], v[92:95]
	v_mfma_f32_16x16x32_bf16 v[88:91], v[156:159], v[206:209], v[88:91]
	v_mfma_f32_16x16x32_bf16 v[76:79], v[132:135], v[226:229], v[76:79]
	v_mfma_f32_16x16x32_bf16 v[72:75], v[156:159], v[226:229], v[72:75]
	s_setprio 0
	s_setprio 1
	v_mfma_f32_16x16x32_bf16 v[116:119], v[160:163], v[186:189], 0
	v_mfma_f32_16x16x32_bf16 v[112:115], v[168:171], v[186:189], 0
	v_mfma_f32_16x16x32_bf16 v[100:103], v[160:163], v[194:197], 0
	v_mfma_f32_16x16x32_bf16 v[96:99], v[168:171], v[194:197], 0
	v_mfma_f32_16x16x32_bf16 v[84:87], v[160:163], v[202:205], 0
	v_mfma_f32_16x16x32_bf16 v[80:83], v[168:171], v[202:205], 0
	v_mfma_f32_16x16x32_bf16 v[68:71], v[160:163], v[222:225], 0
	v_mfma_f32_16x16x32_bf16 v[64:67], v[168:171], v[222:225], 0
	v_mfma_f32_16x16x32_bf16 v[116:119], v[164:167], v[190:193], v[116:119]
	v_mfma_f32_16x16x32_bf16 v[112:115], v[182:185], v[190:193], v[112:115]
	v_mfma_f32_16x16x32_bf16 v[100:103], v[164:167], v[198:201], v[100:103]
	v_mfma_f32_16x16x32_bf16 v[96:99], v[182:185], v[198:201], v[96:99]
	v_mfma_f32_16x16x32_bf16 v[84:87], v[164:167], v[206:209], v[84:87]
	v_mfma_f32_16x16x32_bf16 v[80:83], v[182:185], v[206:209], v[80:83]
	v_mfma_f32_16x16x32_bf16 v[68:71], v[164:167], v[226:229], v[68:71]
	v_mfma_f32_16x16x32_bf16 v[64:67], v[182:185], v[226:229], v[64:67]
	s_setprio 0
	s_barrier
	s_add_i32 s75, s75, s95
	v_lshl_add_u64 v[230:231], s[36:37], 0, v[138:139]
	s_mov_b32 m0, s75
	ds_read_b128 v[186:189], v220 offset:16384
	ds_read_b128 v[190:193], v220 offset:17408
	ds_read_b128 v[194:197], v220 offset:18432
	ds_read_b128 v[198:201], v220 offset:19456
	ds_read_b128 v[202:205], v220 offset:20480
	ds_read_b128 v[206:209], v220 offset:21504
	ds_read_b128 v[222:225], v220 offset:22528
	ds_read_b128 v[226:229], v220 offset:23552
	global_load_lds_dwordx4 v[230:231], off
	s_add_i32 m0, s75, 0x2000
	s_add_u32 s90, s36, 0x40000
	v_lshl_add_u64 v[232:233], s[36:37], 0, v[142:143]
	s_addc_u32 s91, s37, 0
	s_add_i32 s75, s89, s95
	global_load_lds_dwordx4 v[232:233], off
	v_lshl_add_u64 v[234:235], s[90:91], 0, v[138:139]
	s_mov_b32 m0, s75
	v_lshl_add_u64 v[236:237], s[52:53], 0, v[140:141]
	global_load_lds_dwordx4 v[234:235], off
	v_lshl_add_u64 v[234:235], s[90:91], 0, v[142:143]
	s_add_i32 m0, s75, 0x2000
	s_nop 0
	global_load_lds_dwordx4 v[234:235], off
	v_lshl_add_u64 v[234:235], s[52:53], 0, v[136:137]
	s_mov_b32 m0, s56
	s_nop 0
	global_load_lds_dwordx4 v[234:235], off
	s_mov_b32 m0, s57
	s_nop 0
	global_load_lds_dwordx4 v[236:237], off
	s_cmp_lg_u32 s99, 0
	s_cbranch_scc1 .Lrx2a
	s_waitcnt vmcnt(8)
	s_branch .Lrx2b

; #define PG8_STAGE(bufoff, gbase, voff) do { _Pragma("unroll") for (int _i = 0; _i < 2; ++_i) \
;         __builtin_amdgcn_global_load_lds((const GAS unsigned*)((const GAS char*)(gbase) + (voff)[_i]), (LAS unsigned*)(lds + (bufoff) + ldsw + _i * 8192), 16, 0, 0); } while (0)
; #define PG8_LDA(dst, b, h) do { _Pragma("unroll") for (int m = 0; m < 4; ++m) _Pragma("unroll") for (int k = 0; k < 2; ++k) dst[m][k] = *(const LAS bf16x8*)(lds + PG8_SA(b, h) + aoff + m * 2048 + k * 1024); } while (0)
; #define PG8_LDB(dst, b, h) do { _Pragma("unroll") for (int n = 0; n < 2; ++n) _Pragma("unroll") for (int k = 0; k < 2; ++k) dst[n][k] = *(const LAS bf16x8*)(lds + PG8_SB(b, h) + boff + n * 2048 + k * 1024); } while (0)
; #define PG8_MMA(ai, bj, At, Bt) do { __builtin_amdgcn_s_setprio(1); _Pragma("unroll") for (int m = 0; m < 4; ++m) _Pragma("unroll") for (int n = 0; n < 2; ++n) _Pragma("unroll") for (int k = 0; k < 2; ++k) \
;         acc[ai][bj][m][n] = __builtin_amdgcn_mfma_f32_16x16x32_bf16(Bt[n][k], At[m][k], acc[ai][bj][m][n], 0, 0, 0); __builtin_amdgcn_s_setprio(0); } while (0)
; #define PG8_WAIT_V(n) asm volatile("s_waitcnt vmcnt(" #n ")" ::: "memory")
; #define PG8_WAIT_L(n) asm volatile("s_waitcnt lgkmcnt(" #n ")" ::: "memory")
; #define PG8_BAR __builtin_amdgcn_s_barrier()
; #define PG8_SCHED __builtin_amdgcn_sched_barrier(0)
;     ...
;             PG8_WAIT_V(8); PG8_WAIT_L(0); PG8_BAR; PG8_MMA(1, 0, At, B0); PG8_MMA(1, 1, At, B1); PG8_BAR; PG8_SCHED;
;             PG8_LDB(B0, 1, 0); PG8_LDB(B1, 1, 1); PG8_SCHED; PG8_LDA(At, 1, 0); PG8_STAGE(PG8_SA(0, 1), a2 + hstep, voffA);
;             PG8_WAIT_V(8); PG8_WAIT_L(0); PG8_BAR; PG8_MMA(0, 0, At, B0); PG8_MMA(0, 1, At, B1); PG8_BAR; PG8_SCHED;
.Lrx2b:
	s_mov_b32 s99, 0
	s_waitcnt lgkmcnt(0)
	s_barrier
	s_setprio 1
	s_waitcnt lgkmcnt(0)
	v_mfma_f32_16x16x32_bf16 v[60:63], v[128:131], v[186:189], 0
	v_mfma_f32_16x16x32_bf16 v[56:59], v[152:155], v[186:189], 0
	v_mfma_f32_16x16x32_bf16 v[44:47], v[128:131], v[194:197], 0
	v_mfma_f32_16x16x32_bf16 v[40:43], v[152:155], v[194:197], 0
	v_mfma_f32_16x16x32_bf16 v[28:31], v[128:131], v[202:205], 0
	v_mfma_f32_16x16x32_bf16 v[24:27], v[152:155], v[202:205], 0
	v_mfma_f32_16x16x32_bf16 v[12:15], v[128:131], v[222:225], 0
	v_mfma_f32_16x16x32_bf16 v[8:11], v[152:155], v[222:225], 0
	v_mfma_f32_16x16x32_bf16 v[60:63], v[132:135], v[190:193], v[60:63]
	v_mfma_f32_16x16x32_bf16 v[56:59], v[156:159], v[190:193], v[56:59]
	v_mfma_f32_16x16x32_bf16 v[44:47], v[132:135], v[198:201], v[44:47]
	v_mfma_f32_16x16x32_bf16 v[40:43], v[156:159], v[198:201], v[40:43]
	v_mfma_f32_16x16x32_bf16 v[28:31], v[132:135], v[206:209], v[28:31]
	v_mfma_f32_16x16x32_bf16 v[24:27], v[156:159], v[206:209], v[24:27]
	v_mfma_f32_16x16x32_bf16 v[12:15], v[132:135], v[226:229], v[12:15]
	v_mfma_f32_16x16x32_bf16 v[8:11], v[156:159], v[226:229], v[8:11]
	s_setprio 0
	s_setprio 1
	v_mfma_f32_16x16x32_bf16 v[52:55], v[160:163], v[186:189], 0
	v_mfma_f32_16x16x32_bf16 v[48:51], v[168:171], v[186:189], 0
	v_mfma_f32_16x16x32_bf16 v[36:39], v[160:163], v[194:197], 0
	v_mfma_f32_16x16x32_bf16 v[32:35], v[168:171], v[194:197], 0
	v_mfma_f32_16x16x32_bf16 v[20:23], v[160:163], v[202:205], 0
	v_mfma_f32_16x16x32_bf16 v[16:19], v[168:171], v[202:205], 0
	v_mfma_f32_16x16x32_bf16 v[4:7], v[160:163], v[222:225], 0
	v_mfma_f32_16x16x32_bf16 v[0:3], v[168:171], v[222:225], 0
	v_mfma_f32_16x16x32_bf16 v[52:55], v[164:167], v[190:193], v[52:55]
	v_mfma_f32_16x16x32_bf16 v[48:51], v[182:185], v[190:193], v[48:51]
	v_mfma_f32_16x16x32_bf16 v[36:39], v[164:167], v[198:201], v[36:39]
	v_mfma_f32_16x16x32_bf16 v[32:35], v[182:185], v[198:201], v[32:35]
	v_mfma_f32_16x16x32_bf16 v[20:23], v[164:167], v[206:209], v[20:23]
	v_mfma_f32_16x16x32_bf16 v[16:19], v[182:185], v[206:209], v[16:19]
	v_mfma_f32_16x16x32_bf16 v[4:7], v[164:167], v[226:229], v[4:7]
	v_mfma_f32_16x16x32_bf16 v[0:3], v[182:185], v[226:229], v[0:3]
	s_setprio 0
	s_barrier
	s_add_i32 s75, 0, 0x18000
	s_add_i32 s89, 0, 0x1c000
	v_add_u32_e32 v156, s75, v218
	v_add_u32_e32 v172, s89, v218
	ds_read_b128 v[128:131], v156
	ds_read_b128 v[132:135], v156 offset:1024
	ds_read_b128 v[152:155], v156 offset:2048
	ds_read_b128 v[156:159], v156 offset:3072
	ds_read_b128 v[160:163], v172
	ds_read_b128 v[164:167], v172 offset:1024
	ds_read_b128 v[168:171], v172 offset:2048
	ds_read_b128 v[182:185], v172 offset:3072
	s_add_u32 s52, s52, 0x40000
	s_addc_u32 s53, s53, 0
	s_mov_b32 m0, s69
	v_lshl_add_u64 v[238:239], s[52:53], 0, v[136:137]
	ds_read_b128 v[186:189], v220 offset:32768
	ds_read_b128 v[190:193], v220 offset:33792
	ds_read_b128 v[194:197], v220 offset:34816
	ds_read_b128 v[198:201], v220 offset:35840
	ds_read_b128 v[202:205], v220 offset:36864
	ds_read_b128 v[206:209], v220 offset:37888
	ds_read_b128 v[222:225], v220 offset:38912
	ds_read_b128 v[226:229], v220 offset:39936
	global_load_lds_dwordx4 v[238:239], off
	v_lshl_add_u64 v[238:239], s[52:53], 0, v[140:141]
	s_mov_b32 m0, s66
	s_nop 0
	global_load_lds_dwordx4 v[238:239], off
	s_waitcnt vmcnt(8)
	s_waitcnt lgkmcnt(0)
	s_barrier
	s_setprio 1
	s_waitcnt lgkmcnt(0)
	v_mfma_f32_16x16x32_bf16 v[124:127], v[128:131], v[186:189], v[124:127]
	v_mfma_f32_16x16x32_bf16 v[120:123], v[152:155], v[186:189], v[120:123]
	v_mfma_f32_16x16x32_bf16 v[108:111], v[128:131], v[194:197], v[108:111]
	v_mfma_f32_16x16x32_bf16 v[104:107], v[152:155], v[194:197], v[104:107]
	v_mfma_f32_16x16x32_bf16 v[92:95], v[128:131], v[202:205], v[92:95]
	v_mfma_f32_16x16x32_bf16 v[88:91], v[152:155], v[202:205], v[88:91]
	v_mfma_f32_16x16x32_bf16 v[76:79], v[128:131], v[222:225], v[76:79]
	v_mfma_f32_16x16x32_bf16 v[72:75], v[152:155], v[222:225], v[72:75]
	v_mfma_f32_16x16x32_bf16 v[124:127], v[132:135], v[190:193], v[124:127]
	v_mfma_f32_16x16x32_bf16 v[120:123], v[156:159], v[190:193], v[120:123]
	v_mfma_f32_16x16x32_bf16 v[108:111], v[132:135], v[198:201], v[108:111]
	v_mfma_f32_16x16x32_bf16 v[104:107], v[156:159], v[198:201], v[104:107]
	v_mfma_f32_16x16x32_bf16 v[92:95], v[132:135], v[206:209], v[92:95]
	v_mfma_f32_16x16x32_bf16 v[88:91], v[156:159], v[206:209], v[88:91]
	v_mfma_f32_16x16x32_bf16 v[76:79], v[132:135], v[226:229], v[76:79]
	v_mfma_f32_16x16x32_bf16 v[72:75], v[156:159], v[226:229], v[72:75]
	s_setprio 0
	s_setprio 1
	v_mfma_f32_16x16x32_bf16 v[116:119], v[160:163], v[186:189], v[116:119]
	v_mfma_f32_16x16x32_bf16 v[112:115], v[168:171], v[186:189], v[112:115]
	v_mfma_f32_16x16x32_bf16 v[100:103], v[160:163], v[194:197], v[100:103]
	v_mfma_f32_16x16x32_bf16 v[96:99], v[168:171], v[194:197], v[96:99]
	v_mfma_f32_16x16x32_bf16 v[84:87], v[160:163], v[202:205], v[84:87]
	v_mfma_f32_16x16x32_bf16 v[80:83], v[168:171], v[202:205], v[80:83]
	v_mfma_f32_16x16x32_bf16 v[68:71], v[160:163], v[222:225], v[68:71]
	v_mfma_f32_16x16x32_bf16 v[64:67], v[168:171], v[222:225], v[64:67]
	v_mfma_f32_16x16x32_bf16 v[116:119], v[164:167], v[190:193], v[116:119]
	v_mfma_f32_16x16x32_bf16 v[112:115], v[182:185], v[190:193], v[112:115]
	v_mfma_f32_16x16x32_bf16 v[100:103], v[164:167], v[198:201], v[100:103]
	v_mfma_f32_16x16x32_bf16 v[96:99], v[182:185], v[198:201], v[96:99]
	v_mfma_f32_16x16x32_bf16 v[84:87], v[164:167], v[206:209], v[84:87]
	v_mfma_f32_16x16x32_bf16 v[80:83], v[182:185], v[206:209], v[80:83]
	v_mfma_f32_16x16x32_bf16 v[68:71], v[164:167], v[226:229], v[68:71]
	v_mfma_f32_16x16x32_bf16 v[64:67], v[182:185], v[226:229], v[64:67]
	s_setprio 0
	s_barrier
; #define PG8_STAGE(bufoff, gbase, voff) do { _Pragma("unroll") for (int _i = 0; _i < 2; ++_i) \
;         __builtin_amdgcn_global_load_lds((const GAS unsigned*)((const GAS char*)(gbase) + (voff)[_i]), (LAS unsigned*)(lds + (bufoff) + ldsw + _i * 8192), 16, 0, 0); } while (0)
; #define PG8_LDA(dst, b, h) do { _Pragma("unroll") for (int m = 0; m < 4; ++m) _Pragma("unroll") for (int k = 0; k < 2; ++k) dst[m][k] = *(const LAS bf16x8*)(lds + PG8_SA(b, h) + aoff + m * 2048 + k * 1024); } while (0)
; #define PG8_MMA(ai, bj, At, Bt) do { __builtin_amdgcn_s_setprio(1); _Pragma("unroll") for (int m = 0; m < 4; ++m) _Pragma("unroll") for (int n = 0; n < 2; ++n) _Pragma("unroll") for (int k = 0; k < 2; ++k) \
;         acc[ai][bj][m][n] = __builtin_amdgcn_mfma_f32_16x16x32_bf16(Bt[n][k], At[m][k], acc[ai][bj][m][n], 0, 0, 0); __builtin_amdgcn_s_setprio(0); } while (0)
; #define PG8_WAIT_V(n) asm volatile("s_waitcnt vmcnt(" #n ")" ::: "memory")
; #define PG8_WAIT_L(n) asm volatile("s_waitcnt lgkmcnt(" #n ")" ::: "memory")
; #define PG8_BAR __builtin_amdgcn_s_barrier()
; #define PG8_SCHED __builtin_amdgcn_sched_barrier(0)
;     ...
;         for (int t = 0; t < nt; t += 2) {
;     ...
;             PG8_LDA(At, 1, 1); PG8_STAGE(PG8_SB(1, 0), b3, voffB); PG8_STAGE(PG8_SB(1, 1), b3 + hstep, voffB); PG8_STAGE(PG8_SA(1, 0), a3, voffA);
;             PG8_WAIT_V(8); PG8_WAIT_L(0); PG8_BAR; PG8_MMA(1, 0, At, B0); PG8_MMA(1, 1, At, B1); PG8_BAR; PG8_SCHED;
	s_add_i32 s52, s75, s95
	v_lshl_add_u64 v[230:231], v[230:231], 0, s[82:83]
	s_mov_b32 m0, s52
	ds_read_b128 v[186:189], v220 offset:49152
	ds_read_b128 v[190:193], v220 offset:50176
	ds_read_b128 v[194:197], v220 offset:51200
	ds_read_b128 v[198:201], v220 offset:52224
	ds_read_b128 v[202:205], v220 offset:53248
	ds_read_b128 v[206:209], v220 offset:54272
	ds_read_b128 v[222:225], v220 offset:55296
	ds_read_b128 v[226:229], v220 offset:56320
	global_load_lds_dwordx4 v[230:231], off
	s_add_i32 m0, s52, 0x2000
	s_add_u32 s36, s36, 0x40080
	v_lshl_add_u64 v[230:231], v[232:233], 0, s[82:83]
	s_addc_u32 s37, s37, 0
	s_add_i32 s52, s89, s95
	global_load_lds_dwordx4 v[230:231], off
	v_lshl_add_u64 v[230:231], s[36:37], 0, v[138:139]
	s_mov_b32 m0, s52
	s_nop 0
	global_load_lds_dwordx4 v[230:231], off
	v_lshl_add_u64 v[230:231], s[36:37], 0, v[142:143]
	s_add_i32 m0, s52, 0x2000
	s_nop 0
	global_load_lds_dwordx4 v[230:231], off
	v_lshl_add_u64 v[230:231], v[234:235], 0, s[82:83]
	s_mov_b32 m0, s67
	s_nop 0
	global_load_lds_dwordx4 v[230:231], off
	v_lshl_add_u64 v[230:231], v[236:237], 0, s[82:83]
	s_mov_b32 m0, s12
	s_nop 0
	global_load_lds_dwordx4 v[230:231], off
	s_waitcnt vmcnt(8)
	s_waitcnt lgkmcnt(0)
	s_barrier
	s_setprio 1
	s_waitcnt lgkmcnt(0)
	v_mfma_f32_16x16x32_bf16 v[60:63], v[128:131], v[186:189], v[60:63]
	v_mfma_f32_16x16x32_bf16 v[56:59], v[152:155], v[186:189], v[56:59]
	v_mfma_f32_16x16x32_bf16 v[44:47], v[128:131], v[194:197], v[44:47]
	v_mfma_f32_16x16x32_bf16 v[40:43], v[152:155], v[194:197], v[40:43]
	v_mfma_f32_16x16x32_bf16 v[28:31], v[128:131], v[202:205], v[28:31]
	v_mfma_f32_16x16x32_bf16 v[24:27], v[152:155], v[202:205], v[24:27]
	v_mfma_f32_16x16x32_bf16 v[12:15], v[128:131], v[222:225], v[12:15]
	v_mfma_f32_16x16x32_bf16 v[8:11], v[152:155], v[222:225], v[8:11]
	v_mfma_f32_16x16x32_bf16 v[60:63], v[132:135], v[190:193], v[60:63]
	v_mfma_f32_16x16x32_bf16 v[56:59], v[156:159], v[190:193], v[56:59]
	v_mfma_f32_16x16x32_bf16 v[44:47], v[132:135], v[198:201], v[44:47]
	v_mfma_f32_16x16x32_bf16 v[40:43], v[156:159], v[198:201], v[40:43]
	v_mfma_f32_16x16x32_bf16 v[28:31], v[132:135], v[206:209], v[28:31]
	v_mfma_f32_16x16x32_bf16 v[24:27], v[156:159], v[206:209], v[24:27]
	v_mfma_f32_16x16x32_bf16 v[12:15], v[132:135], v[226:229], v[12:15]
	v_mfma_f32_16x16x32_bf16 v[8:11], v[156:159], v[226:229], v[8:11]
	s_setprio 0
	s_setprio 1
	v_mfma_f32_16x16x32_bf16 v[52:55], v[160:163], v[186:189], v[52:55]
	v_mfma_f32_16x16x32_bf16 v[48:51], v[168:171], v[186:189], v[48:51]
	v_mfma_f32_16x16x32_bf16 v[36:39], v[160:163], v[194:197], v[36:39]
	v_mfma_f32_16x16x32_bf16 v[32:35], v[168:171], v[194:197], v[32:35]
	v_mfma_f32_16x16x32_bf16 v[20:23], v[160:163], v[202:205], v[20:23]
	v_mfma_f32_16x16x32_bf16 v[16:19], v[168:171], v[202:205], v[16:19]
	v_mfma_f32_16x16x32_bf16 v[4:7], v[160:163], v[222:225], v[4:7]
	v_mfma_f32_16x16x32_bf16 v[0:3], v[168:171], v[222:225], v[0:3]
	v_mfma_f32_16x16x32_bf16 v[52:55], v[164:167], v[190:193], v[52:55]
	v_mfma_f32_16x16x32_bf16 v[48:51], v[182:185], v[190:193], v[48:51]
	v_mfma_f32_16x16x32_bf16 v[36:39], v[164:167], v[198:201], v[36:39]
	v_mfma_f32_16x16x32_bf16 v[32:35], v[182:185], v[198:201], v[32:35]
	v_mfma_f32_16x16x32_bf16 v[20:23], v[164:167], v[206:209], v[20:23]
	v_mfma_f32_16x16x32_bf16 v[16:19], v[182:185], v[206:209], v[16:19]
	v_mfma_f32_16x16x32_bf16 v[4:7], v[164:167], v[226:229], v[4:7]
	v_mfma_f32_16x16x32_bf16 v[0:3], v[182:185], v[226:229], v[0:3]
	s_setprio 0
	s_barrier
	s_add_i32 s65, s65, 2
	s_add_u32 s63, s63, 0x100
	s_addc_u32 s64, s64, 0
	s_add_u32 s34, s34, 0x100
	s_addc_u32 s35, s35, 0

; #define GAS __attribute__((address_space(1)))
; #define EPI_FOR_ROWS for (int ai = 0; ai < 2; ++ai) _Pragma("unroll") for (int m = 0; m < 4; ++m)
;     __device__ __forceinline__ void operator()(Acc& acc, const Unit& u, int wr, int wc, int fr, int fq, LAS unsigned char* lds) const {
;     ...
;         if (grp == 0) {
; #pragma unroll
;             EPI_FOR_ROWS { const int row = row0 + ai * 128 + m * 16; GAS float* d = nullptr;
;                 if (sample) { const int rr = row - MPAD, b = rr >> 6, i = rr & 63; if (i >= DSEQ - 15) d = out + O_PS + (((size_t)layer * DBATCH + b) * 15 + (i - (DSEQ - 15))) * 1024; }
;                 else if (row < MP) { const int b = row / LP, t = row - b * LP; if (t >= LP - 15) d = out + O_PP + (((size_t)layer * BATCH + b) * 15 + (t - (LP - 15))) * 1024; }
.Lep_done:
	s_mov_b32 s99, 1
	s_cmp_lt_u32 s74, 4
	s_cbranch_scc0 .LBB0_364
	v_or_b32_e32 v158, 16, v154
	v_or_b32_e32 v160, 32, v154
	v_or_b32_e32 v162, 48, v154
	v_add_u32_e32 v164, 0x80, v154
	v_add_u32_e32 v166, 0x90, v154
	v_add_u32_e32 v168, 0xa0, v154
	v_add_u32_e32 v170, 0xb0, v154
	s_movk_i32 s24, 0x4080
	v_cmp_gt_i32_e32 vcc, s24, v154
	s_xor_b64 s[24:25], s[36:37], -1
	s_and_b64 s[52:53], s[24:25], vcc
	v_mov_b64_e32 v[128:129], 0
	s_and_saveexec_b64 s[34:35], s[52:53]
	s_cbranch_execz .LBB0_305
	s_mov_b32 s52, 0xfe03f81
	v_mul_hi_i32 v128, v154, s52
	v_lshrrev_b32_e32 v129, 31, v128
	v_ashrrev_i32_e32 v128, 7, v128
	v_add_u32_e32 v131, v128, v129
	s_movk_i32 s52, 0xf7f0
	v_mad_i32_i24 v130, v131, s52, v154
	s_movk_i32 s52, 0x800
	v_cmp_lt_i32_e32 vcc, s52, v130
	v_mov_b64_e32 v[128:129], 0
	s_and_saveexec_b64 s[52:53], vcc
	s_cbranch_execz .LBB0_304
	v_readlane_b32 s62, v240, 35
	v_add_u32_e32 v172, 0xfffff7ff, v130
	s_nop 0
	v_add_u32_e32 v128, s62, v131
	v_mul_hi_i32_i24_e32 v129, 15, v128
	v_mul_i32_i24_e32 v128, 15, v128
	v_lshl_add_u64 v[128:129], v[128:129], 0, v[172:173]
	v_readlane_b32 s62, v240, 33
	v_lshlrev_b64 v[128:129], 12, v[128:129]
	v_readlane_b32 s63, v240, 34
	s_nop 1
	v_lshl_add_u64 v[128:129], s[62:63], 0, v[128:129]
